# static s_setprio 1 for waves 4-7 during the attention phase on top of hand-scheduled MLA+diff attention
# speedup vs baseline: 1.0179x; 1.0010x over previous
; __global__ void __launch_bounds__(512, 2) mega_fwd(Params p) {
;     ...
;         if constexpr (PH_MASK & 16) {
;             const float lam_init = 0.8f - 0.6f * expf(-0.3f * (float)l);
;             float a = p.in[12][l * 64 + lane] * p.in[13][l * 64 + lane], c = p.in[14][l * 64 + lane] * p.in[15][l * 64 + lane];
;             a = wave_sum(a); c = wave_sum(c);
;             const float lam = expf(a) - expf(c) + lam_init;
;             for (int rep_ = 0; rep_ < EXP_ATT_REPS; ++rep_) {
;             if constexpr (ATT_MASK & 1) for (int it = vcu; it < 512; it += G) { const int bh = it >> 3, qb = it & 7; diff_unit(p, lds, l, lam, lam_init, bh >> 2, bh & 3, qb, tid, lane, wave); }
.LBB0_1778:
	s_or_b64 exec, exec, s[0:1]
	v_readfirstlane_b32 s98, v230
	s_nop 0
	s_lshr_b32 s98, s98, 8
	s_cmp_eq_u32 s98, 0
	s_cbranch_scc1 .Latt_prio_skip
	s_setprio 1
.Latt_prio_skip:
	v_readlane_b32 s0, v255, 46
	v_readlane_b32 s36, v252, 26
	v_readlane_b32 s44, v252, 34
	v_or_b32_e32 v176, s0, v231
	s_waitcnt lgkmcnt(0)
	v_lshlrev_b64 v[0:1], 2, v[176:177]
	v_readlane_b32 s45, v252, 35
	v_readlane_b32 s46, v252, 36
	v_readlane_b32 s47, v252, 37
	v_lshl_add_u64 v[2:3], s[44:45], 0, v[0:1]
	s_barrier
	global_load_dword v4, v[2:3], off
	v_lshl_add_u64 v[2:3], s[46:47], 0, v[0:1]
	global_load_dword v5, v[2:3], off
	v_readlane_b32 s48, v252, 38
	v_readlane_b32 s49, v252, 39
	v_readlane_b32 s50, v252, 40
	v_readlane_b32 s51, v252, 41
	v_lshl_add_u64 v[2:3], s[48:49], 0, v[0:1]
	global_load_dword v2, v[2:3], off
	v_lshl_add_u64 v[0:1], s[50:51], 0, v[0:1]
	global_load_dword v3, v[0:1], off
	v_and_b32_e32 v0, 64, v234
	v_add_u32_e32 v1, 64, v0
	v_xor_b32_e32 v0, 1, v234
	v_cmp_lt_i32_e32 vcc, v0, v1
	v_readlane_b32 s1, v255, 47
	v_readlane_b32 s0, v254, 28
	v_cndmask_b32_e32 v0, v234, v0, vcc
	v_lshlrev_b32_e32 v8, 2, v0
	v_readlane_b32 s1, v254, 29
	v_readlane_b32 s37, v252, 27
	v_readlane_b32 s38, v252, 28
	v_readlane_b32 s39, v252, 29
	v_readlane_b32 s40, v252, 30
	v_readlane_b32 s41, v252, 31
	v_readlane_b32 s42, v252, 32
	v_readlane_b32 s43, v252, 33
	s_waitcnt vmcnt(2)
	v_mul_f32_e32 v6, v4, v5
	ds_bpermute_b32 v0, v8, v6
	s_waitcnt lgkmcnt(0)
	v_fmac_f32_e32 v0, v4, v5
	v_xor_b32_e32 v4, 2, v234
	v_cmp_lt_i32_e32 vcc, v4, v1
	s_waitcnt vmcnt(0)
	v_mul_f32_e32 v7, v2, v3
	ds_bpermute_b32 v7, v8, v7
	v_cndmask_b32_e32 v4, v234, v4, vcc
	v_lshlrev_b32_e32 v4, 2, v4
	ds_bpermute_b32 v5, v4, v0
	s_waitcnt lgkmcnt(1)
	v_fmac_f32_e32 v7, v2, v3
	ds_bpermute_b32 v2, v4, v7
	s_waitcnt lgkmcnt(1)
	v_add_f32_e32 v0, v0, v5
	v_xor_b32_e32 v5, 4, v234
	v_cmp_lt_i32_e32 vcc, v5, v1
	s_waitcnt lgkmcnt(0)
	v_add_f32_e32 v2, v7, v2
	v_cndmask_b32_e32 v5, v234, v5, vcc
	v_lshlrev_b32_e32 v5, 2, v5
	ds_bpermute_b32 v6, v5, v0
	ds_bpermute_b32 v3, v5, v2
	s_waitcnt lgkmcnt(1)
	v_add_f32_e32 v0, v0, v6
	v_xor_b32_e32 v6, 8, v234
	v_cmp_lt_i32_e32 vcc, v6, v1
	s_waitcnt lgkmcnt(0)
	v_add_f32_e32 v2, v2, v3
	v_cndmask_b32_e32 v6, v234, v6, vcc
	v_lshlrev_b32_e32 v6, 2, v6
	ds_bpermute_b32 v9, v6, v0
	ds_bpermute_b32 v3, v6, v2
	s_waitcnt lgkmcnt(1)
	v_add_f32_e32 v0, v0, v9
	v_xor_b32_e32 v9, 16, v234
	v_cmp_lt_i32_e32 vcc, v9, v1
	s_waitcnt lgkmcnt(0)
	v_add_f32_e32 v2, v2, v3
	v_cndmask_b32_e32 v9, v234, v9, vcc
	v_lshlrev_b32_e32 v204, 2, v9
	ds_bpermute_b32 v9, v204, v0
	ds_bpermute_b32 v3, v204, v2
	s_waitcnt lgkmcnt(1)
	v_add_f32_e32 v0, v0, v9
	v_xor_b32_e32 v9, 32, v234
	v_cmp_lt_i32_e32 vcc, v9, v1
	s_waitcnt lgkmcnt(0)
	v_add_f32_e32 v2, v2, v3
	v_cndmask_b32_e32 v1, v234, v9, vcc
	v_lshlrev_b32_e32 v205, 2, v1
	ds_bpermute_b32 v1, v205, v0
	ds_bpermute_b32 v3, v205, v2
	s_andn2_b64 vcc, exec, s[0:1]
	s_cbranch_vccnz .LBB0_1909
	v_cvt_f32_u32_e32 v4, s91
	s_mov_b32 s0, 0x3fb8aa3b
	s_waitcnt lgkmcnt(1)
	v_add_f32_e32 v0, v0, v1
	v_mul_f32_e32 v1, 0x3fb8aa3b, v0
	v_mul_f32_e32 v4, 0xbe99999a, v4
	v_mul_f32_e32 v5, 0x3fb8aa3b, v4
	v_fma_f32 v6, v4, s0, -v5
	v_rndne_f32_e32 v7, v5
	v_fmac_f32_e32 v6, 0x32a5705f, v4
	v_sub_f32_e32 v5, v5, v7
	v_add_f32_e32 v5, v5, v6
	v_cvt_i32_f32_e32 v7, v7
	v_exp_f32_e32 v5, v5
	v_fma_f32 v6, v0, s0, -v1
	v_fmac_f32_e32 v6, 0x32a5705f, v0
	s_mov_b32 s1, 0xc2ce8ed0
	v_ldexp_f32 v5, v5, v7
	v_rndne_f32_e32 v7, v1
	v_sub_f32_e32 v1, v1, v7
	v_add_f32_e32 v1, v1, v6
	v_exp_f32_e32 v1, v1
	v_cvt_i32_f32_e32 v6, v7
	v_cmp_ngt_f32_e32 vcc, s1, v4
	s_mov_b32 s10, 0x42b17218
	v_mov_b32_e32 v7, 0x7f800000
	v_cndmask_b32_e32 v5, 0, v5, vcc
	v_cmp_nlt_f32_e32 vcc, s10, v4
	s_waitcnt lgkmcnt(0)
	v_add_f32_e32 v2, v2, v3
	v_mul_f32_e32 v3, 0x3fb8aa3b, v2
	v_cndmask_b32_e32 v4, v7, v5, vcc
	v_mov_b32_e32 v5, 0x3f4ccccd
	v_fmamk_f32 v4, v4, 0xbf19999a, v5
	v_ldexp_f32 v1, v1, v6
	v_fma_f32 v5, v2, s0, -v3
	v_rndne_f32_e32 v6, v3
	v_fmac_f32_e32 v5, 0x32a5705f, v2
	v_sub_f32_e32 v3, v3, v6
	v_add_f32_e32 v3, v3, v5
	v_exp_f32_e32 v3, v3
	v_cvt_i32_f32_e32 v5, v6
	v_cmp_ngt_f32_e32 vcc, s1, v0
	s_lshl_b32 s96, s91, 7
	v_sub_f32_e32 v207, 1.0, v4
	v_cndmask_b32_e32 v1, 0, v1, vcc
	v_cmp_nlt_f32_e32 vcc, s10, v0
	v_readlane_b32 s12, v252, 1
	s_nop 0
	v_cndmask_b32_e32 v0, v7, v1, vcc
	v_ldexp_f32 v1, v3, v5
	v_cmp_ngt_f32_e32 vcc, s1, v2
	s_lshl_b64 s[0:1], s[96:97], 2
	s_add_u32 s14, s52, s0
	v_cndmask_b32_e32 v1, 0, v1, vcc
	v_cmp_nlt_f32_e32 vcc, s10, v2
	s_addc_u32 s15, s53, s1
	s_nop 0
	v_cndmask_b32_e32 v1, v7, v1, vcc
	v_sub_f32_e32 v0, v0, v1
	v_add_f32_e32 v206, v4, v0
	s_branch .LBB0_1781

; __device__ __forceinline__ unsigned xb_add(unsigned* p, unsigned v) { return __hip_atomic_fetch_add(p, v, __ATOMIC_RELAXED, __HIP_MEMORY_SCOPE_AGENT); }
; __device__ __forceinline__ void xcd_barrier(const XcdBarrier& b) {
;     asm volatile("s_waitcnt vmcnt(0)" ::: "memory");
;     __syncthreads();
;     if (threadIdx.x == 0) {
;         unsigned* bar = b.bar;
;         __builtin_amdgcn_s_waitcnt(0);
;         unsigned nloc = b.st[0], nx = b.st[1];
;         if (nloc == 0u) { xcd_barrier_complete(bar, b.x, nloc, nx); b.st[0] = nloc; b.st[1] = nx; }
;         const unsigned old = xb_add(&bar[XB_XSUB(b.x)], 1u);
.LBB0_1910:
	s_setprio 0
	s_waitcnt vmcnt(0)
	s_waitcnt vmcnt(0) lgkmcnt(0)
	s_barrier
	s_mov_b64 s[0:1], exec
	v_readlane_b32 s10, v252, 18
	v_readlane_b32 s11, v252, 19
	s_and_b64 s[10:11], s[0:1], s[10:11]
	s_mov_b64 exec, s[10:11]
	s_cbranch_execz .LBB0_2027
	v_readlane_b32 s10, v255, 16
	s_waitcnt vmcnt(0) expcnt(0) lgkmcnt(0)
	s_nop 0
	v_mov_b32_e32 v0, s10
	ds_read_b32 v2, v0
	v_readlane_b32 s10, v255, 17
	s_waitcnt lgkmcnt(0)
	v_cmp_ne_u32_e32 vcc, 0, v2
	v_mov_b32_e32 v0, s10
	ds_read_b32 v0, v0
	s_cbranch_vccnz .LBB0_1991
	s_mov_b32 s12, 1
	s_branch .LBB0_1979
